# speedup vs baseline: 1.0073x; 1.0035x over previous
; template <bool FP8>
; __device__ __forceinline__ void gemm_tile_256(const u16* __restrict__ A, int lda, const u16* __restrict__ Bt, int ldb,
;                                               int K, char* smem, f32x4 (&acc)[8][4]) {
;     ...
;   __syncthreads();
.LBB0_130:
	s_setprio 3
	s_mov_b64 s[10:11], 0
	s_barrier

; template <bool FP8>
; __device__ __forceinline__ void gemm_tile_256(const u16* __restrict__ A, int lda, const u16* __restrict__ Bt, int ldb,
;                                               int K, char* smem, f32x4 (&acc)[8][4]) {
;     ...
;   __syncthreads();
.LBB0_136:
	s_setprio 3
	s_barrier

; __device__ __forceinline__ float lo_bf(unsigned u) { return __uint_as_float(u << 16); }
; __device__ __forceinline__ float hi_bf(unsigned u) { return __uint_as_float(u & 0xffff0000u); }
; __device__ __forceinline__ void phase_merge(const Params& p, char* smem) {
;     ...
;       int mt2 = mt, nt2 = nt;
;       asm volatile("" : "+s"(mt2), "+s"(nt2));
; #pragma unroll
;       for (int m = 0; m < 8; ++m)
; #pragma unroll
;         for (int n = 0; n < 4; ++n) {
;           const size_t row = (size_t)mt2 * 256 + wr * 128 + m * 16 + fr;
;           const int col = nt2 * 128 + wc * 64 + n * 16 + fq * 4;
;           const uint2 g = *(const uint2*)(G + row * 2048 + col);
;           float v0 = acc[m][n][0] * lo_bf(g.x), v1 = acc[m][n][1] * hi_bf(g.x);
;           float v2 = acc[m][n][2] * lo_bf(g.y), v3 = acc[m][n][3] * hi_bf(g.y);
;           if (pass) {
;             const uint2 pm = *(const uint2*)(mg + row * 2048 + col);
;             v0 += lo_bf(pm.x); v1 += hi_bf(pm.x); v2 += lo_bf(pm.y); v3 += hi_bf(pm.y);
;           }
;           uint2 o; o.x = pack2(v0, v1); o.y = pack2(v2, v3);
;           *(uint2*)(mg + row * 2048 + col) = o;
;         }
.LBB0_953:
	s_setprio 3
	s_and_b64 s[6:7], s[8:9], exec
	s_cselect_b32 s6, s27, 0x30c00000
	s_add_u32 s10, s54, s6
	s_mov_b32 s49, s45
	s_mov_b32 s6, s46
	s_addc_u32 s11, s55, 0
	s_barrier
	s_ashr_i32 s7, s6, 31
	s_lshl_b64 s[6:7], s[6:7], 19
	s_waitcnt vmcnt(0)
	v_lshl_add_u64 v[106:107], s[6:7], 0, v[176:177]
	v_lshl_or_b32 v104, s49, 7, v192
	v_add_lshl_u32 v226, v106, v104, 1
	s_andn2_b64 vcc, exec, s[12:13]
	s_cbranch_vccnz .Lmg_p0
	s_add_u32 s98, s10, 0x0
	s_addc_u32 s99, s11, 0
	s_add_u32 s100, s40, 0x0
	s_addc_u32 s101, s41, 0
	global_load_dwordx2 v[104:105], v226, s[98:99]
	global_load_dwordx2 v[106:107], v226, s[98:99] offset:32
	global_load_dwordx2 v[108:109], v226, s[98:99] offset:64
	global_load_dwordx2 v[110:111], v226, s[98:99] offset:96
	s_add_u32 s98, s98, 0x10000
	s_addc_u32 s99, s99, 0
	global_load_dwordx2 v[112:113], v226, s[98:99]
	global_load_dwordx2 v[114:115], v226, s[98:99] offset:32
	global_load_dwordx2 v[116:117], v226, s[98:99] offset:64
	global_load_dwordx2 v[118:119], v226, s[98:99] offset:96
	s_add_u32 s98, s98, 0x10000
	s_addc_u32 s99, s99, 0
	global_load_dwordx2 v[124:125], v226, s[98:99]
	global_load_dwordx2 v[126:127], v226, s[98:99] offset:32
	global_load_dwordx2 v[128:129], v226, s[98:99] offset:64
	global_load_dwordx2 v[130:131], v226, s[98:99] offset:96
	s_add_u32 s98, s98, 0x10000
	s_addc_u32 s99, s99, 0
	global_load_dwordx2 v[132:133], v226, s[98:99]
	global_load_dwordx2 v[134:135], v226, s[98:99] offset:32
	global_load_dwordx2 v[136:137], v226, s[98:99] offset:64
	global_load_dwordx2 v[138:139], v226, s[98:99] offset:96
	global_load_dwordx2 v[140:141], v226, s[100:101]
	global_load_dwordx2 v[142:143], v226, s[100:101] offset:32
	global_load_dwordx2 v[144:145], v226, s[100:101] offset:64
	global_load_dwordx2 v[146:147], v226, s[100:101] offset:96
	s_add_u32 s100, s100, 0x10000
	s_addc_u32 s101, s101, 0
	global_load_dwordx2 v[148:149], v226, s[100:101]
	global_load_dwordx2 v[150:151], v226, s[100:101] offset:32
	global_load_dwordx2 v[152:153], v226, s[100:101] offset:64
	global_load_dwordx2 v[154:155], v226, s[100:101] offset:96
	s_add_u32 s100, s100, 0x10000
	s_addc_u32 s101, s101, 0
	global_load_dwordx2 v[198:199], v226, s[100:101]
	global_load_dwordx2 v[200:201], v226, s[100:101] offset:32
	global_load_dwordx2 v[202:203], v226, s[100:101] offset:64
	global_load_dwordx2 v[204:205], v226, s[100:101] offset:96
	s_add_u32 s100, s100, 0x10000
	s_addc_u32 s101, s101, 0
	global_load_dwordx2 v[206:207], v226, s[100:101]
	global_load_dwordx2 v[208:209], v226, s[100:101] offset:32
	global_load_dwordx2 v[210:211], v226, s[100:101] offset:64
	global_load_dwordx2 v[212:213], v226, s[100:101] offset:96
	s_waitcnt vmcnt(0)
	s_add_u32 s100, s40, 0x0
	s_addc_u32 s101, s41, 0
	v_lshlrev_b32_e32 v218, 16, v104
	v_and_b32_e32 v219, 0xffff0000, v104
	v_lshlrev_b32_e32 v220, 16, v105
	v_and_b32_e32 v221, 0xffff0000, v105
	v_pk_mul_f32 v[218:219], v[172:173], v[218:219]
	v_pk_mul_f32 v[220:221], v[174:175], v[220:221]
	v_lshlrev_b32_e32 v222, 16, v140
	v_and_b32_e32 v223, 0xffff0000, v140
	v_lshlrev_b32_e32 v224, 16, v141
	v_and_b32_e32 v225, 0xffff0000, v141
	v_pk_add_f32 v[218:219], v[218:219], v[222:223]
	v_pk_add_f32 v[220:221], v[220:221], v[224:225]
	v_cvt_pk_bf16_f32 v104, v218, v219
	v_cvt_pk_bf16_f32 v105, v220, v221
	global_store_dwordx2 v226, v[104:105], s[100:101]
	v_lshlrev_b32_e32 v218, 16, v106
	v_and_b32_e32 v219, 0xffff0000, v106
	v_lshlrev_b32_e32 v220, 16, v107
	v_and_b32_e32 v221, 0xffff0000, v107
	v_pk_mul_f32 v[218:219], v[168:169], v[218:219]
	v_pk_mul_f32 v[220:221], v[170:171], v[220:221]
	v_lshlrev_b32_e32 v222, 16, v142
	v_and_b32_e32 v223, 0xffff0000, v142
	v_lshlrev_b32_e32 v224, 16, v143
	v_and_b32_e32 v225, 0xffff0000, v143
	v_pk_add_f32 v[218:219], v[218:219], v[222:223]
	v_pk_add_f32 v[220:221], v[220:221], v[224:225]
	v_cvt_pk_bf16_f32 v106, v218, v219
	v_cvt_pk_bf16_f32 v107, v220, v221
	global_store_dwordx2 v226, v[106:107], s[100:101] offset:32
	v_lshlrev_b32_e32 v218, 16, v108
	v_and_b32_e32 v219, 0xffff0000, v108
	v_lshlrev_b32_e32 v220, 16, v109
	v_and_b32_e32 v221, 0xffff0000, v109
	v_pk_mul_f32 v[218:219], v[164:165], v[218:219]
	v_pk_mul_f32 v[220:221], v[166:167], v[220:221]
	v_lshlrev_b32_e32 v222, 16, v144
	v_and_b32_e32 v223, 0xffff0000, v144
	v_lshlrev_b32_e32 v224, 16, v145
	v_and_b32_e32 v225, 0xffff0000, v145
	v_pk_add_f32 v[218:219], v[218:219], v[222:223]
	v_pk_add_f32 v[220:221], v[220:221], v[224:225]
	v_cvt_pk_bf16_f32 v108, v218, v219
	v_cvt_pk_bf16_f32 v109, v220, v221
	global_store_dwordx2 v226, v[108:109], s[100:101] offset:64
	v_lshlrev_b32_e32 v218, 16, v110
	v_and_b32_e32 v219, 0xffff0000, v110
	v_lshlrev_b32_e32 v220, 16, v111
	v_and_b32_e32 v221, 0xffff0000, v111
	v_pk_mul_f32 v[218:219], v[160:161], v[218:219]
	v_pk_mul_f32 v[220:221], v[162:163], v[220:221]
	v_lshlrev_b32_e32 v222, 16, v146
	v_and_b32_e32 v223, 0xffff0000, v146
	v_lshlrev_b32_e32 v224, 16, v147
	v_and_b32_e32 v225, 0xffff0000, v147
	v_pk_add_f32 v[218:219], v[218:219], v[222:223]
	v_pk_add_f32 v[220:221], v[220:221], v[224:225]
	v_cvt_pk_bf16_f32 v110, v218, v219
	v_cvt_pk_bf16_f32 v111, v220, v221
	global_store_dwordx2 v226, v[110:111], s[100:101] offset:96
	s_add_u32 s100, s100, 0x10000
	s_addc_u32 s101, s101, 0
	v_lshlrev_b32_e32 v218, 16, v112
	v_and_b32_e32 v219, 0xffff0000, v112
	v_lshlrev_b32_e32 v220, 16, v113
	v_and_b32_e32 v221, 0xffff0000, v113
	v_pk_mul_f32 v[218:219], v[156:157], v[218:219]
	v_pk_mul_f32 v[220:221], v[158:159], v[220:221]
	v_lshlrev_b32_e32 v222, 16, v148
	v_and_b32_e32 v223, 0xffff0000, v148
	v_lshlrev_b32_e32 v224, 16, v149
	v_and_b32_e32 v225, 0xffff0000, v149
; __device__ __forceinline__ float lo_bf(unsigned u) { return __uint_as_float(u << 16); }
; __device__ __forceinline__ float hi_bf(unsigned u) { return __uint_as_float(u & 0xffff0000u); }
; __device__ __forceinline__ void phase_merge(const Params& p, char* smem) {
;     ...
;       int mt2 = mt, nt2 = nt;
;       asm volatile("" : "+s"(mt2), "+s"(nt2));
; #pragma unroll
;       for (int m = 0; m < 8; ++m)
; #pragma unroll
;         for (int n = 0; n < 4; ++n) {
;           const size_t row = (size_t)mt2 * 256 + wr * 128 + m * 16 + fr;
;           const int col = nt2 * 128 + wc * 64 + n * 16 + fq * 4;
;           const uint2 g = *(const uint2*)(G + row * 2048 + col);
;           float v0 = acc[m][n][0] * lo_bf(g.x), v1 = acc[m][n][1] * hi_bf(g.x);
;           float v2 = acc[m][n][2] * lo_bf(g.y), v3 = acc[m][n][3] * hi_bf(g.y);
;           if (pass) {
;             const uint2 pm = *(const uint2*)(mg + row * 2048 + col);
;             v0 += lo_bf(pm.x); v1 += hi_bf(pm.x); v2 += lo_bf(pm.y); v3 += hi_bf(pm.y);
;           }
;           uint2 o; o.x = pack2(v0, v1); o.y = pack2(v2, v3);
;           *(uint2*)(mg + row * 2048 + col) = o;
;         }
	v_pk_add_f32 v[218:219], v[218:219], v[222:223]
	v_pk_add_f32 v[220:221], v[220:221], v[224:225]
	v_cvt_pk_bf16_f32 v112, v218, v219
	v_cvt_pk_bf16_f32 v113, v220, v221
	global_store_dwordx2 v226, v[112:113], s[100:101]
	v_lshlrev_b32_e32 v218, 16, v114
	v_and_b32_e32 v219, 0xffff0000, v114
	v_lshlrev_b32_e32 v220, 16, v115
	v_and_b32_e32 v221, 0xffff0000, v115
	v_pk_mul_f32 v[218:219], v[120:121], v[218:219]
	v_pk_mul_f32 v[220:221], v[122:123], v[220:221]
	v_lshlrev_b32_e32 v222, 16, v150
	v_and_b32_e32 v223, 0xffff0000, v150
	v_lshlrev_b32_e32 v224, 16, v151
	v_and_b32_e32 v225, 0xffff0000, v151
	v_pk_add_f32 v[218:219], v[218:219], v[222:223]
	v_pk_add_f32 v[220:221], v[220:221], v[224:225]
	v_cvt_pk_bf16_f32 v114, v218, v219
	v_cvt_pk_bf16_f32 v115, v220, v221
	global_store_dwordx2 v226, v[114:115], s[100:101] offset:32
	v_lshlrev_b32_e32 v218, 16, v116
	v_and_b32_e32 v219, 0xffff0000, v116
	v_lshlrev_b32_e32 v220, 16, v117
	v_and_b32_e32 v221, 0xffff0000, v117
	v_pk_mul_f32 v[218:219], v[100:101], v[218:219]
	v_pk_mul_f32 v[220:221], v[102:103], v[220:221]
	v_lshlrev_b32_e32 v222, 16, v152
	v_and_b32_e32 v223, 0xffff0000, v152
	v_lshlrev_b32_e32 v224, 16, v153
	v_and_b32_e32 v225, 0xffff0000, v153
	v_pk_add_f32 v[218:219], v[218:219], v[222:223]
	v_pk_add_f32 v[220:221], v[220:221], v[224:225]
	v_cvt_pk_bf16_f32 v116, v218, v219
	v_cvt_pk_bf16_f32 v117, v220, v221
	global_store_dwordx2 v226, v[116:117], s[100:101] offset:64
	v_lshlrev_b32_e32 v218, 16, v118
	v_and_b32_e32 v219, 0xffff0000, v118
	v_lshlrev_b32_e32 v220, 16, v119
	v_and_b32_e32 v221, 0xffff0000, v119
	v_pk_mul_f32 v[218:219], v[96:97], v[218:219]
	v_pk_mul_f32 v[220:221], v[98:99], v[220:221]
	v_lshlrev_b32_e32 v222, 16, v154
	v_and_b32_e32 v223, 0xffff0000, v154
	v_lshlrev_b32_e32 v224, 16, v155
	v_and_b32_e32 v225, 0xffff0000, v155
	v_pk_add_f32 v[218:219], v[218:219], v[222:223]
	v_pk_add_f32 v[220:221], v[220:221], v[224:225]
	v_cvt_pk_bf16_f32 v118, v218, v219
	v_cvt_pk_bf16_f32 v119, v220, v221
	global_store_dwordx2 v226, v[118:119], s[100:101] offset:96
	s_add_u32 s100, s100, 0x10000
	s_addc_u32 s101, s101, 0
	v_lshlrev_b32_e32 v218, 16, v124
	v_and_b32_e32 v219, 0xffff0000, v124
	v_lshlrev_b32_e32 v220, 16, v125
	v_and_b32_e32 v221, 0xffff0000, v125
	v_pk_mul_f32 v[218:219], v[92:93], v[218:219]
	v_pk_mul_f32 v[220:221], v[94:95], v[220:221]
	v_lshlrev_b32_e32 v222, 16, v198
	v_and_b32_e32 v223, 0xffff0000, v198
	v_lshlrev_b32_e32 v224, 16, v199
	v_and_b32_e32 v225, 0xffff0000, v199
	v_pk_add_f32 v[218:219], v[218:219], v[222:223]
	v_pk_add_f32 v[220:221], v[220:221], v[224:225]
	v_cvt_pk_bf16_f32 v124, v218, v219
	v_cvt_pk_bf16_f32 v125, v220, v221
	global_store_dwordx2 v226, v[124:125], s[100:101]
	v_lshlrev_b32_e32 v218, 16, v126
	v_and_b32_e32 v219, 0xffff0000, v126
	v_lshlrev_b32_e32 v220, 16, v127
	v_and_b32_e32 v221, 0xffff0000, v127
	v_pk_mul_f32 v[218:219], v[88:89], v[218:219]
	v_pk_mul_f32 v[220:221], v[90:91], v[220:221]
	v_lshlrev_b32_e32 v222, 16, v200
	v_and_b32_e32 v223, 0xffff0000, v200
	v_lshlrev_b32_e32 v224, 16, v201
	v_and_b32_e32 v225, 0xffff0000, v201
	v_pk_add_f32 v[218:219], v[218:219], v[222:223]
	v_pk_add_f32 v[220:221], v[220:221], v[224:225]
	v_cvt_pk_bf16_f32 v126, v218, v219
	v_cvt_pk_bf16_f32 v127, v220, v221
	global_store_dwordx2 v226, v[126:127], s[100:101] offset:32
	v_lshlrev_b32_e32 v218, 16, v128
	v_and_b32_e32 v219, 0xffff0000, v128
	v_lshlrev_b32_e32 v220, 16, v129
	v_and_b32_e32 v221, 0xffff0000, v129
	v_pk_mul_f32 v[218:219], v[84:85], v[218:219]
	v_pk_mul_f32 v[220:221], v[86:87], v[220:221]
	v_lshlrev_b32_e32 v222, 16, v202
	v_and_b32_e32 v223, 0xffff0000, v202
	v_lshlrev_b32_e32 v224, 16, v203
	v_and_b32_e32 v225, 0xffff0000, v203
	v_pk_add_f32 v[218:219], v[218:219], v[222:223]
	v_pk_add_f32 v[220:221], v[220:221], v[224:225]
	v_cvt_pk_bf16_f32 v128, v218, v219
	v_cvt_pk_bf16_f32 v129, v220, v221
	global_store_dwordx2 v226, v[128:129], s[100:101] offset:64
	v_lshlrev_b32_e32 v218, 16, v130
	v_and_b32_e32 v219, 0xffff0000, v130
	v_lshlrev_b32_e32 v220, 16, v131
	v_and_b32_e32 v221, 0xffff0000, v131
	v_pk_mul_f32 v[218:219], v[80:81], v[218:219]
	v_pk_mul_f32 v[220:221], v[82:83], v[220:221]
	v_lshlrev_b32_e32 v222, 16, v204
	v_and_b32_e32 v223, 0xffff0000, v204
	v_lshlrev_b32_e32 v224, 16, v205
	v_and_b32_e32 v225, 0xffff0000, v205
	v_pk_add_f32 v[218:219], v[218:219], v[222:223]
	v_pk_add_f32 v[220:221], v[220:221], v[224:225]
	v_cvt_pk_bf16_f32 v130, v218, v219
	v_cvt_pk_bf16_f32 v131, v220, v221
	global_store_dwordx2 v226, v[130:131], s[100:101] offset:96
	s_add_u32 s100, s100, 0x10000
	s_addc_u32 s101, s101, 0
	v_lshlrev_b32_e32 v218, 16, v132
	v_and_b32_e32 v219, 0xffff0000, v132
	v_lshlrev_b32_e32 v220, 16, v133
	v_and_b32_e32 v221, 0xffff0000, v133
	v_pk_mul_f32 v[218:219], v[76:77], v[218:219]
	v_pk_mul_f32 v[220:221], v[78:79], v[220:221]
	v_lshlrev_b32_e32 v222, 16, v206
	v_and_b32_e32 v223, 0xffff0000, v206
	v_lshlrev_b32_e32 v224, 16, v207
	v_and_b32_e32 v225, 0xffff0000, v207
	v_pk_add_f32 v[218:219], v[218:219], v[222:223]
	v_pk_add_f32 v[220:221], v[220:221], v[224:225]
	v_cvt_pk_bf16_f32 v132, v218, v219
	v_cvt_pk_bf16_f32 v133, v220, v221
	global_store_dwordx2 v226, v[132:133], s[100:101]
	v_lshlrev_b32_e32 v218, 16, v134
	v_and_b32_e32 v219, 0xffff0000, v134
	v_lshlrev_b32_e32 v220, 16, v135
	v_and_b32_e32 v221, 0xffff0000, v135
	v_pk_mul_f32 v[218:219], v[72:73], v[218:219]
	v_pk_mul_f32 v[220:221], v[74:75], v[220:221]
	v_lshlrev_b32_e32 v222, 16, v208
	v_and_b32_e32 v223, 0xffff0000, v208
	v_lshlrev_b32_e32 v224, 16, v209
	v_and_b32_e32 v225, 0xffff0000, v209
	v_pk_add_f32 v[218:219], v[218:219], v[222:223]
; __device__ __forceinline__ float lo_bf(unsigned u) { return __uint_as_float(u << 16); }
; __device__ __forceinline__ float hi_bf(unsigned u) { return __uint_as_float(u & 0xffff0000u); }
; __device__ __forceinline__ void phase_merge(const Params& p, char* smem) {
;     ...
;       int mt2 = mt, nt2 = nt;
;       asm volatile("" : "+s"(mt2), "+s"(nt2));
; #pragma unroll
;       for (int m = 0; m < 8; ++m)
; #pragma unroll
;         for (int n = 0; n < 4; ++n) {
;           const size_t row = (size_t)mt2 * 256 + wr * 128 + m * 16 + fr;
;           const int col = nt2 * 128 + wc * 64 + n * 16 + fq * 4;
;           const uint2 g = *(const uint2*)(G + row * 2048 + col);
;           float v0 = acc[m][n][0] * lo_bf(g.x), v1 = acc[m][n][1] * hi_bf(g.x);
;           float v2 = acc[m][n][2] * lo_bf(g.y), v3 = acc[m][n][3] * hi_bf(g.y);
;           if (pass) {
;             const uint2 pm = *(const uint2*)(mg + row * 2048 + col);
;             v0 += lo_bf(pm.x); v1 += hi_bf(pm.x); v2 += lo_bf(pm.y); v3 += hi_bf(pm.y);
;           }
;           uint2 o; o.x = pack2(v0, v1); o.y = pack2(v2, v3);
;           *(uint2*)(mg + row * 2048 + col) = o;
;         }
	v_pk_add_f32 v[220:221], v[220:221], v[224:225]
	v_cvt_pk_bf16_f32 v134, v218, v219
	v_cvt_pk_bf16_f32 v135, v220, v221
	global_store_dwordx2 v226, v[134:135], s[100:101] offset:32
	v_lshlrev_b32_e32 v218, 16, v136
	v_and_b32_e32 v219, 0xffff0000, v136
	v_lshlrev_b32_e32 v220, 16, v137
	v_and_b32_e32 v221, 0xffff0000, v137
	v_pk_mul_f32 v[218:219], v[68:69], v[218:219]
	v_pk_mul_f32 v[220:221], v[70:71], v[220:221]
	v_lshlrev_b32_e32 v222, 16, v210
	v_and_b32_e32 v223, 0xffff0000, v210
	v_lshlrev_b32_e32 v224, 16, v211
	v_and_b32_e32 v225, 0xffff0000, v211
	v_pk_add_f32 v[218:219], v[218:219], v[222:223]
	v_pk_add_f32 v[220:221], v[220:221], v[224:225]
	v_cvt_pk_bf16_f32 v136, v218, v219
	v_cvt_pk_bf16_f32 v137, v220, v221
	global_store_dwordx2 v226, v[136:137], s[100:101] offset:64
	v_lshlrev_b32_e32 v218, 16, v138
	v_and_b32_e32 v219, 0xffff0000, v138
	v_lshlrev_b32_e32 v220, 16, v139
	v_and_b32_e32 v221, 0xffff0000, v139
	v_pk_mul_f32 v[218:219], v[64:65], v[218:219]
	v_pk_mul_f32 v[220:221], v[66:67], v[220:221]
	v_lshlrev_b32_e32 v222, 16, v212
	v_and_b32_e32 v223, 0xffff0000, v212
	v_lshlrev_b32_e32 v224, 16, v213
	v_and_b32_e32 v225, 0xffff0000, v213
	v_pk_add_f32 v[218:219], v[218:219], v[222:223]
	v_pk_add_f32 v[220:221], v[220:221], v[224:225]
	v_cvt_pk_bf16_f32 v138, v218, v219
	v_cvt_pk_bf16_f32 v139, v220, v221
	global_store_dwordx2 v226, v[138:139], s[100:101] offset:96
	s_add_u32 s98, s10, 0x40000
	s_addc_u32 s99, s11, 0
	s_add_u32 s100, s40, 0x40000
	s_addc_u32 s101, s41, 0
	global_load_dwordx2 v[104:105], v226, s[98:99]
	global_load_dwordx2 v[106:107], v226, s[98:99] offset:32
	global_load_dwordx2 v[108:109], v226, s[98:99] offset:64
	global_load_dwordx2 v[110:111], v226, s[98:99] offset:96
	s_add_u32 s98, s98, 0x10000
	s_addc_u32 s99, s99, 0
	global_load_dwordx2 v[112:113], v226, s[98:99]
	global_load_dwordx2 v[114:115], v226, s[98:99] offset:32
	global_load_dwordx2 v[116:117], v226, s[98:99] offset:64
	global_load_dwordx2 v[118:119], v226, s[98:99] offset:96
	s_add_u32 s98, s98, 0x10000
	s_addc_u32 s99, s99, 0
	global_load_dwordx2 v[124:125], v226, s[98:99]
	global_load_dwordx2 v[126:127], v226, s[98:99] offset:32
	global_load_dwordx2 v[128:129], v226, s[98:99] offset:64
	global_load_dwordx2 v[130:131], v226, s[98:99] offset:96
	s_add_u32 s98, s98, 0x10000
	s_addc_u32 s99, s99, 0
	global_load_dwordx2 v[132:133], v226, s[98:99]
	global_load_dwordx2 v[134:135], v226, s[98:99] offset:32
	global_load_dwordx2 v[136:137], v226, s[98:99] offset:64
	global_load_dwordx2 v[138:139], v226, s[98:99] offset:96
	global_load_dwordx2 v[140:141], v226, s[100:101]
	global_load_dwordx2 v[142:143], v226, s[100:101] offset:32
	global_load_dwordx2 v[144:145], v226, s[100:101] offset:64
	global_load_dwordx2 v[146:147], v226, s[100:101] offset:96
	s_add_u32 s100, s100, 0x10000
	s_addc_u32 s101, s101, 0
	global_load_dwordx2 v[148:149], v226, s[100:101]
	global_load_dwordx2 v[150:151], v226, s[100:101] offset:32
	global_load_dwordx2 v[152:153], v226, s[100:101] offset:64
	global_load_dwordx2 v[154:155], v226, s[100:101] offset:96
	s_add_u32 s100, s100, 0x10000
	s_addc_u32 s101, s101, 0
	global_load_dwordx2 v[198:199], v226, s[100:101]
	global_load_dwordx2 v[200:201], v226, s[100:101] offset:32
	global_load_dwordx2 v[202:203], v226, s[100:101] offset:64
	global_load_dwordx2 v[204:205], v226, s[100:101] offset:96
	s_add_u32 s100, s100, 0x10000
	s_addc_u32 s101, s101, 0
	global_load_dwordx2 v[206:207], v226, s[100:101]
	global_load_dwordx2 v[208:209], v226, s[100:101] offset:32
	global_load_dwordx2 v[210:211], v226, s[100:101] offset:64
	global_load_dwordx2 v[212:213], v226, s[100:101] offset:96
	s_waitcnt vmcnt(0)
	s_add_u32 s100, s40, 0x40000
	s_addc_u32 s101, s41, 0
	v_lshlrev_b32_e32 v218, 16, v104
	v_and_b32_e32 v219, 0xffff0000, v104
	v_lshlrev_b32_e32 v220, 16, v105
	v_and_b32_e32 v221, 0xffff0000, v105
	v_pk_mul_f32 v[218:219], v[60:61], v[218:219]
	v_pk_mul_f32 v[220:221], v[62:63], v[220:221]
	v_lshlrev_b32_e32 v222, 16, v140
	v_and_b32_e32 v223, 0xffff0000, v140
	v_lshlrev_b32_e32 v224, 16, v141
	v_and_b32_e32 v225, 0xffff0000, v141
	v_pk_add_f32 v[218:219], v[218:219], v[222:223]
	v_pk_add_f32 v[220:221], v[220:221], v[224:225]
	v_cvt_pk_bf16_f32 v104, v218, v219
	v_cvt_pk_bf16_f32 v105, v220, v221
	global_store_dwordx2 v226, v[104:105], s[100:101]
	v_lshlrev_b32_e32 v218, 16, v106
	v_and_b32_e32 v219, 0xffff0000, v106
	v_lshlrev_b32_e32 v220, 16, v107
	v_and_b32_e32 v221, 0xffff0000, v107
	v_pk_mul_f32 v[218:219], v[56:57], v[218:219]
	v_pk_mul_f32 v[220:221], v[58:59], v[220:221]
	v_lshlrev_b32_e32 v222, 16, v142
	v_and_b32_e32 v223, 0xffff0000, v142
	v_lshlrev_b32_e32 v224, 16, v143
	v_and_b32_e32 v225, 0xffff0000, v143
	v_pk_add_f32 v[218:219], v[218:219], v[222:223]
	v_pk_add_f32 v[220:221], v[220:221], v[224:225]
	v_cvt_pk_bf16_f32 v106, v218, v219
	v_cvt_pk_bf16_f32 v107, v220, v221
	global_store_dwordx2 v226, v[106:107], s[100:101] offset:32
	v_lshlrev_b32_e32 v218, 16, v108
	v_and_b32_e32 v219, 0xffff0000, v108
	v_lshlrev_b32_e32 v220, 16, v109
	v_and_b32_e32 v221, 0xffff0000, v109
	v_pk_mul_f32 v[218:219], v[52:53], v[218:219]
	v_pk_mul_f32 v[220:221], v[54:55], v[220:221]
	v_lshlrev_b32_e32 v222, 16, v144
	v_and_b32_e32 v223, 0xffff0000, v144
	v_lshlrev_b32_e32 v224, 16, v145
	v_and_b32_e32 v225, 0xffff0000, v145
	v_pk_add_f32 v[218:219], v[218:219], v[222:223]
	v_pk_add_f32 v[220:221], v[220:221], v[224:225]
	v_cvt_pk_bf16_f32 v108, v218, v219
	v_cvt_pk_bf16_f32 v109, v220, v221
	global_store_dwordx2 v226, v[108:109], s[100:101] offset:64
	v_lshlrev_b32_e32 v218, 16, v110
	v_and_b32_e32 v219, 0xffff0000, v110
; __device__ __forceinline__ float lo_bf(unsigned u) { return __uint_as_float(u << 16); }
; __device__ __forceinline__ float hi_bf(unsigned u) { return __uint_as_float(u & 0xffff0000u); }
; __device__ __forceinline__ void phase_merge(const Params& p, char* smem) {
;     ...
;       int mt2 = mt, nt2 = nt;
;       asm volatile("" : "+s"(mt2), "+s"(nt2));
; #pragma unroll
;       for (int m = 0; m < 8; ++m)
; #pragma unroll
;         for (int n = 0; n < 4; ++n) {
;           const size_t row = (size_t)mt2 * 256 + wr * 128 + m * 16 + fr;
;           const int col = nt2 * 128 + wc * 64 + n * 16 + fq * 4;
;           const uint2 g = *(const uint2*)(G + row * 2048 + col);
;           float v0 = acc[m][n][0] * lo_bf(g.x), v1 = acc[m][n][1] * hi_bf(g.x);
;           float v2 = acc[m][n][2] * lo_bf(g.y), v3 = acc[m][n][3] * hi_bf(g.y);
;           if (pass) {
;             const uint2 pm = *(const uint2*)(mg + row * 2048 + col);
;             v0 += lo_bf(pm.x); v1 += hi_bf(pm.x); v2 += lo_bf(pm.y); v3 += hi_bf(pm.y);
;           }
;           uint2 o; o.x = pack2(v0, v1); o.y = pack2(v2, v3);
;           *(uint2*)(mg + row * 2048 + col) = o;
;         }
	v_lshlrev_b32_e32 v220, 16, v111
	v_and_b32_e32 v221, 0xffff0000, v111
	v_pk_mul_f32 v[218:219], v[48:49], v[218:219]
	v_pk_mul_f32 v[220:221], v[50:51], v[220:221]
	v_lshlrev_b32_e32 v222, 16, v146
	v_and_b32_e32 v223, 0xffff0000, v146
	v_lshlrev_b32_e32 v224, 16, v147
	v_and_b32_e32 v225, 0xffff0000, v147
	v_pk_add_f32 v[218:219], v[218:219], v[222:223]
	v_pk_add_f32 v[220:221], v[220:221], v[224:225]
	v_cvt_pk_bf16_f32 v110, v218, v219
	v_cvt_pk_bf16_f32 v111, v220, v221
	global_store_dwordx2 v226, v[110:111], s[100:101] offset:96
	s_add_u32 s100, s100, 0x10000
	s_addc_u32 s101, s101, 0
	v_lshlrev_b32_e32 v218, 16, v112
	v_and_b32_e32 v219, 0xffff0000, v112
	v_lshlrev_b32_e32 v220, 16, v113
	v_and_b32_e32 v221, 0xffff0000, v113
	v_pk_mul_f32 v[218:219], v[44:45], v[218:219]
	v_pk_mul_f32 v[220:221], v[46:47], v[220:221]
	v_lshlrev_b32_e32 v222, 16, v148
	v_and_b32_e32 v223, 0xffff0000, v148
	v_lshlrev_b32_e32 v224, 16, v149
	v_and_b32_e32 v225, 0xffff0000, v149
	v_pk_add_f32 v[218:219], v[218:219], v[222:223]
	v_pk_add_f32 v[220:221], v[220:221], v[224:225]
	v_cvt_pk_bf16_f32 v112, v218, v219
	v_cvt_pk_bf16_f32 v113, v220, v221
	global_store_dwordx2 v226, v[112:113], s[100:101]
	v_lshlrev_b32_e32 v218, 16, v114
	v_and_b32_e32 v219, 0xffff0000, v114
	v_lshlrev_b32_e32 v220, 16, v115
	v_and_b32_e32 v221, 0xffff0000, v115
	v_pk_mul_f32 v[218:219], v[40:41], v[218:219]
	v_pk_mul_f32 v[220:221], v[42:43], v[220:221]
	v_lshlrev_b32_e32 v222, 16, v150
	v_and_b32_e32 v223, 0xffff0000, v150
	v_lshlrev_b32_e32 v224, 16, v151
	v_and_b32_e32 v225, 0xffff0000, v151
	v_pk_add_f32 v[218:219], v[218:219], v[222:223]
	v_pk_add_f32 v[220:221], v[220:221], v[224:225]
	v_cvt_pk_bf16_f32 v114, v218, v219
	v_cvt_pk_bf16_f32 v115, v220, v221
	global_store_dwordx2 v226, v[114:115], s[100:101] offset:32
	v_lshlrev_b32_e32 v218, 16, v116
	v_and_b32_e32 v219, 0xffff0000, v116
	v_lshlrev_b32_e32 v220, 16, v117
	v_and_b32_e32 v221, 0xffff0000, v117
	v_pk_mul_f32 v[218:219], v[36:37], v[218:219]
	v_pk_mul_f32 v[220:221], v[38:39], v[220:221]
	v_lshlrev_b32_e32 v222, 16, v152
	v_and_b32_e32 v223, 0xffff0000, v152
	v_lshlrev_b32_e32 v224, 16, v153
	v_and_b32_e32 v225, 0xffff0000, v153
	v_pk_add_f32 v[218:219], v[218:219], v[222:223]
	v_pk_add_f32 v[220:221], v[220:221], v[224:225]
	v_cvt_pk_bf16_f32 v116, v218, v219
	v_cvt_pk_bf16_f32 v117, v220, v221
	global_store_dwordx2 v226, v[116:117], s[100:101] offset:64
	v_lshlrev_b32_e32 v218, 16, v118
	v_and_b32_e32 v219, 0xffff0000, v118
	v_lshlrev_b32_e32 v220, 16, v119
	v_and_b32_e32 v221, 0xffff0000, v119
	v_pk_mul_f32 v[218:219], v[32:33], v[218:219]
	v_pk_mul_f32 v[220:221], v[34:35], v[220:221]
	v_lshlrev_b32_e32 v222, 16, v154
	v_and_b32_e32 v223, 0xffff0000, v154
	v_lshlrev_b32_e32 v224, 16, v155
	v_and_b32_e32 v225, 0xffff0000, v155
	v_pk_add_f32 v[218:219], v[218:219], v[222:223]
	v_pk_add_f32 v[220:221], v[220:221], v[224:225]
	v_cvt_pk_bf16_f32 v118, v218, v219
	v_cvt_pk_bf16_f32 v119, v220, v221
	global_store_dwordx2 v226, v[118:119], s[100:101] offset:96
	s_add_u32 s100, s100, 0x10000
	s_addc_u32 s101, s101, 0
	v_lshlrev_b32_e32 v218, 16, v124
	v_and_b32_e32 v219, 0xffff0000, v124
	v_lshlrev_b32_e32 v220, 16, v125
	v_and_b32_e32 v221, 0xffff0000, v125
	v_pk_mul_f32 v[218:219], v[28:29], v[218:219]
	v_pk_mul_f32 v[220:221], v[30:31], v[220:221]
	v_lshlrev_b32_e32 v222, 16, v198
	v_and_b32_e32 v223, 0xffff0000, v198
	v_lshlrev_b32_e32 v224, 16, v199
	v_and_b32_e32 v225, 0xffff0000, v199
	v_pk_add_f32 v[218:219], v[218:219], v[222:223]
	v_pk_add_f32 v[220:221], v[220:221], v[224:225]
	v_cvt_pk_bf16_f32 v124, v218, v219
	v_cvt_pk_bf16_f32 v125, v220, v221
	global_store_dwordx2 v226, v[124:125], s[100:101]
	v_lshlrev_b32_e32 v218, 16, v126
	v_and_b32_e32 v219, 0xffff0000, v126
	v_lshlrev_b32_e32 v220, 16, v127
	v_and_b32_e32 v221, 0xffff0000, v127
	v_pk_mul_f32 v[218:219], v[24:25], v[218:219]
	v_pk_mul_f32 v[220:221], v[26:27], v[220:221]
	v_lshlrev_b32_e32 v222, 16, v200
	v_and_b32_e32 v223, 0xffff0000, v200
	v_lshlrev_b32_e32 v224, 16, v201
	v_and_b32_e32 v225, 0xffff0000, v201
; __device__ __forceinline__ float lo_bf(unsigned u) { return __uint_as_float(u << 16); }
; __device__ __forceinline__ float hi_bf(unsigned u) { return __uint_as_float(u & 0xffff0000u); }
; __device__ __forceinline__ void phase_merge(const Params& p, char* smem) {
;     ...
;         for (int n = 0; n < 4; ++n) {
;           const size_t row = (size_t)mt2 * 256 + wr * 128 + m * 16 + fr;
;           const int col = nt2 * 128 + wc * 64 + n * 16 + fq * 4;
;           const uint2 g = *(const uint2*)(G + row * 2048 + col);
;           float v0 = acc[m][n][0] * lo_bf(g.x), v1 = acc[m][n][1] * hi_bf(g.x);
;           float v2 = acc[m][n][2] * lo_bf(g.y), v3 = acc[m][n][3] * hi_bf(g.y);
;           if (pass) {
;             const uint2 pm = *(const uint2*)(mg + row * 2048 + col);
;             v0 += lo_bf(pm.x); v1 += hi_bf(pm.x); v2 += lo_bf(pm.y); v3 += hi_bf(pm.y);
;           }
;           uint2 o; o.x = pack2(v0, v1); o.y = pack2(v2, v3);
;           *(uint2*)(mg + row * 2048 + col) = o;
;         }
	v_pk_add_f32 v[218:219], v[218:219], v[222:223]
	v_pk_add_f32 v[220:221], v[220:221], v[224:225]
	v_cvt_pk_bf16_f32 v126, v218, v219
	v_cvt_pk_bf16_f32 v127, v220, v221
	global_store_dwordx2 v226, v[126:127], s[100:101] offset:32
	v_lshlrev_b32_e32 v218, 16, v128
	v_and_b32_e32 v219, 0xffff0000, v128
	v_lshlrev_b32_e32 v220, 16, v129
	v_and_b32_e32 v221, 0xffff0000, v129
	v_pk_mul_f32 v[218:219], v[20:21], v[218:219]
	v_pk_mul_f32 v[220:221], v[22:23], v[220:221]
	v_lshlrev_b32_e32 v222, 16, v202
	v_and_b32_e32 v223, 0xffff0000, v202
	v_lshlrev_b32_e32 v224, 16, v203
	v_and_b32_e32 v225, 0xffff0000, v203
	v_pk_add_f32 v[218:219], v[218:219], v[222:223]
	v_pk_add_f32 v[220:221], v[220:221], v[224:225]
	v_cvt_pk_bf16_f32 v128, v218, v219
	v_cvt_pk_bf16_f32 v129, v220, v221
	global_store_dwordx2 v226, v[128:129], s[100:101] offset:64
	v_lshlrev_b32_e32 v218, 16, v130
	v_and_b32_e32 v219, 0xffff0000, v130
	v_lshlrev_b32_e32 v220, 16, v131
	v_and_b32_e32 v221, 0xffff0000, v131
	v_pk_mul_f32 v[218:219], v[16:17], v[218:219]
	v_pk_mul_f32 v[220:221], v[18:19], v[220:221]
	v_lshlrev_b32_e32 v222, 16, v204
	v_and_b32_e32 v223, 0xffff0000, v204
	v_lshlrev_b32_e32 v224, 16, v205
	v_and_b32_e32 v225, 0xffff0000, v205
	v_pk_add_f32 v[218:219], v[218:219], v[222:223]
	v_pk_add_f32 v[220:221], v[220:221], v[224:225]
	v_cvt_pk_bf16_f32 v130, v218, v219
	v_cvt_pk_bf16_f32 v131, v220, v221
	global_store_dwordx2 v226, v[130:131], s[100:101] offset:96
	s_add_u32 s100, s100, 0x10000
	s_addc_u32 s101, s101, 0
	v_lshlrev_b32_e32 v218, 16, v132
	v_and_b32_e32 v219, 0xffff0000, v132
	v_lshlrev_b32_e32 v220, 16, v133
	v_and_b32_e32 v221, 0xffff0000, v133
	v_pk_mul_f32 v[218:219], v[12:13], v[218:219]
	v_pk_mul_f32 v[220:221], v[14:15], v[220:221]
	v_lshlrev_b32_e32 v222, 16, v206
	v_and_b32_e32 v223, 0xffff0000, v206
	v_lshlrev_b32_e32 v224, 16, v207
	v_and_b32_e32 v225, 0xffff0000, v207
	v_pk_add_f32 v[218:219], v[218:219], v[222:223]
	v_pk_add_f32 v[220:221], v[220:221], v[224:225]
	v_cvt_pk_bf16_f32 v132, v218, v219
	v_cvt_pk_bf16_f32 v133, v220, v221
	global_store_dwordx2 v226, v[132:133], s[100:101]
	v_lshlrev_b32_e32 v218, 16, v134
	v_and_b32_e32 v219, 0xffff0000, v134
	v_lshlrev_b32_e32 v220, 16, v135
	v_and_b32_e32 v221, 0xffff0000, v135
	v_pk_mul_f32 v[218:219], v[8:9], v[218:219]
	v_pk_mul_f32 v[220:221], v[10:11], v[220:221]
	v_lshlrev_b32_e32 v222, 16, v208
	v_and_b32_e32 v223, 0xffff0000, v208
	v_lshlrev_b32_e32 v224, 16, v209
	v_and_b32_e32 v225, 0xffff0000, v209
	v_pk_add_f32 v[218:219], v[218:219], v[222:223]
	v_pk_add_f32 v[220:221], v[220:221], v[224:225]
	v_cvt_pk_bf16_f32 v134, v218, v219
	v_cvt_pk_bf16_f32 v135, v220, v221
	global_store_dwordx2 v226, v[134:135], s[100:101] offset:32
	v_lshlrev_b32_e32 v218, 16, v136
	v_and_b32_e32 v219, 0xffff0000, v136
	v_lshlrev_b32_e32 v220, 16, v137
	v_and_b32_e32 v221, 0xffff0000, v137
	v_pk_mul_f32 v[218:219], v[4:5], v[218:219]
	v_pk_mul_f32 v[220:221], v[6:7], v[220:221]
	v_lshlrev_b32_e32 v222, 16, v210
	v_and_b32_e32 v223, 0xffff0000, v210
	v_lshlrev_b32_e32 v224, 16, v211
	v_and_b32_e32 v225, 0xffff0000, v211
	v_pk_add_f32 v[218:219], v[218:219], v[222:223]
	v_pk_add_f32 v[220:221], v[220:221], v[224:225]
	v_cvt_pk_bf16_f32 v136, v218, v219
	v_cvt_pk_bf16_f32 v137, v220, v221
	global_store_dwordx2 v226, v[136:137], s[100:101] offset:64
	v_lshlrev_b32_e32 v218, 16, v138
	v_and_b32_e32 v219, 0xffff0000, v138
	v_lshlrev_b32_e32 v220, 16, v139
	v_and_b32_e32 v221, 0xffff0000, v139
	v_pk_mul_f32 v[218:219], v[0:1], v[218:219]
	v_pk_mul_f32 v[220:221], v[2:3], v[220:221]
	v_lshlrev_b32_e32 v222, 16, v212
	v_and_b32_e32 v223, 0xffff0000, v212
	v_lshlrev_b32_e32 v224, 16, v213
	v_and_b32_e32 v225, 0xffff0000, v213
	v_pk_add_f32 v[218:219], v[218:219], v[222:223]
	v_pk_add_f32 v[220:221], v[220:221], v[224:225]
	v_cvt_pk_bf16_f32 v138, v218, v219
	v_cvt_pk_bf16_f32 v139, v220, v221
	global_store_dwordx2 v226, v[138:139], s[100:101] offset:96
	s_add_i32 s44, s44, s3
	s_add_i32 s14, s14, s3
	s_cmpk_lt_u32 s44, 0x100
	s_cbranch_scc0 .LBB0_1017
	s_branch .LBB0_947

; __device__ __forceinline__ void phase_outproj(const Params& p, char* smem) {
;     ...
;     const int b = (mt * 256) >> 14;
; #pragma unroll
;     for (int n = 0; n < 4; ++n) {
;       const int col = nt * 128 + wc * 64 + n * 16 + fq * 4;
;       const float4 g1 = *(const float4*)(mod + b * 12288 + 4096 + col);
; #pragma unroll
;       for (int m = 0; m < 8; ++m) {
;         const size_t row = (size_t)mt * 256 + wr * 128 + m * 16 + fr;
;         const float4 xv = *(const float4*)(p.x + row * D + col);
;         float4 o;
;         o.x = ALPHA * xv.x + (1.f + g1.x) * acc[m][n][0];
;         o.y = ALPHA * xv.y + (1.f + g1.y) * acc[m][n][1];
;         o.z = ALPHA * xv.z + (1.f + g1.z) * acc[m][n][2];
;         o.w = ALPHA * xv.w + (1.f + g1.w) * acc[m][n][3];
;         *(float4*)(p.out + row * D + col) = o;
;       }
;     }
.LBB0_1030:
	s_setprio 3
	s_lshl_b32 s0, s21, 19
	v_readlane_b32 s64, v253, 16
	v_readlane_b32 s65, v253, 17
	s_waitcnt vmcnt(0)
	v_lshl_add_u64 v[92:93], s[0:1], 0, v[176:177]
	v_lshl_or_b32 v178, s24, 9, v192
	v_lshlrev_b32_e32 v132, 2, v92
	v_add_u32_e32 v132, v132, v178
	s_mov_b64 s[8:9], s[64:65]
	s_barrier
	global_load_dwordx4 v[92:95], v178, s[4:5]
	global_load_dwordx4 v[96:99], v178, s[4:5] offset:64
	global_load_dwordx4 v[148:151], v178, s[4:5] offset:128
	global_load_dwordx4 v[136:139], v178, s[4:5] offset:192
	s_mov_b64 s[98:99], s[8:9]
	global_load_dwordx4 v[104:107], v132, s[98:99]
	global_load_dwordx4 v[108:111], v132, s[98:99] offset:64
	s_add_u32 s98, s98, 0x20000
	s_addc_u32 s99, s99, 0
	global_load_dwordx4 v[112:115], v132, s[98:99]
	global_load_dwordx4 v[116:119], v132, s[98:99] offset:64
	s_add_u32 s98, s98, 0x20000
	s_addc_u32 s99, s99, 0
	global_load_dwordx4 v[120:123], v132, s[98:99]
	global_load_dwordx4 v[124:127], v132, s[98:99] offset:64
	s_add_u32 s98, s98, 0x20000
	s_addc_u32 s99, s99, 0
	global_load_dwordx4 v[128:131], v132, s[98:99]
	global_load_dwordx4 v[198:201], v132, s[98:99] offset:64
	s_add_u32 s98, s98, 0x20000
	s_addc_u32 s99, s99, 0
	global_load_dwordx4 v[202:205], v132, s[98:99]
	global_load_dwordx4 v[206:209], v132, s[98:99] offset:64
	s_add_u32 s98, s98, 0x20000
	s_addc_u32 s99, s99, 0
	global_load_dwordx4 v[210:213], v132, s[98:99]
	global_load_dwordx4 v[220:223], v132, s[98:99] offset:64
	s_add_u32 s98, s98, 0x20000
	s_addc_u32 s99, s99, 0
	global_load_dwordx4 v[224:227], v132, s[98:99]
	global_load_dwordx4 v[228:231], v132, s[98:99] offset:64
	s_add_u32 s98, s98, 0x20000
	s_addc_u32 s99, s99, 0
	global_load_dwordx4 v[232:235], v132, s[98:99]
	global_load_dwordx4 v[236:239], v132, s[98:99] offset:64
	s_waitcnt vmcnt(0)
	v_pk_add_f32 v[92:93], v[92:93], 1.0 op_sel_hi:[1,0]
	v_pk_add_f32 v[94:95], v[94:95], 1.0 op_sel_hi:[1,0]
	v_pk_add_f32 v[96:97], v[96:97], 1.0 op_sel_hi:[1,0]
	v_pk_add_f32 v[98:99], v[98:99], 1.0 op_sel_hi:[1,0]
	v_pk_add_f32 v[148:149], v[148:149], 1.0 op_sel_hi:[1,0]
	v_pk_add_f32 v[150:151], v[150:151], 1.0 op_sel_hi:[1,0]
	v_pk_add_f32 v[136:137], v[136:137], 1.0 op_sel_hi:[1,0]
	v_pk_add_f32 v[138:139], v[138:139], 1.0 op_sel_hi:[1,0]
	s_mov_b64 s[100:101], s[52:53]
	v_pk_mul_f32 v[104:105], v[104:105], s[6:7] op_sel_hi:[1,0]
	v_pk_mul_f32 v[106:107], v[106:107], s[6:7] op_sel_hi:[1,0]
	v_pk_fma_f32 v[104:105], v[172:173], v[92:93], v[104:105]
	v_pk_fma_f32 v[106:107], v[174:175], v[94:95], v[106:107]
	v_pk_mul_f32 v[108:109], v[108:109], s[6:7] op_sel_hi:[1,0]
	v_pk_mul_f32 v[110:111], v[110:111], s[6:7] op_sel_hi:[1,0]
	v_pk_fma_f32 v[108:109], v[152:153], v[96:97], v[108:109]
	v_pk_fma_f32 v[110:111], v[154:155], v[98:99], v[110:111]
	global_store_dwordx4 v132, v[104:107], s[100:101]
	global_store_dwordx4 v132, v[108:111], s[100:101] offset:64
	s_add_u32 s100, s100, 0x20000
	s_addc_u32 s101, s101, 0
	v_pk_mul_f32 v[112:113], v[112:113], s[6:7] op_sel_hi:[1,0]
	v_pk_mul_f32 v[114:115], v[114:115], s[6:7] op_sel_hi:[1,0]
	v_pk_fma_f32 v[112:113], v[168:169], v[92:93], v[112:113]
	v_pk_fma_f32 v[114:115], v[170:171], v[94:95], v[114:115]
	v_pk_mul_f32 v[116:117], v[116:117], s[6:7] op_sel_hi:[1,0]
	v_pk_mul_f32 v[118:119], v[118:119], s[6:7] op_sel_hi:[1,0]
	v_pk_fma_f32 v[116:117], v[140:141], v[96:97], v[116:117]
	v_pk_fma_f32 v[118:119], v[142:143], v[98:99], v[118:119]
	global_store_dwordx4 v132, v[112:115], s[100:101]
	global_store_dwordx4 v132, v[116:119], s[100:101] offset:64
	s_add_u32 s100, s100, 0x20000
	s_addc_u32 s101, s101, 0
	v_pk_mul_f32 v[120:121], v[120:121], s[6:7] op_sel_hi:[1,0]
	v_pk_mul_f32 v[122:123], v[122:123], s[6:7] op_sel_hi:[1,0]
	v_pk_fma_f32 v[120:121], v[164:165], v[92:93], v[120:121]
	v_pk_fma_f32 v[122:123], v[166:167], v[94:95], v[122:123]
	v_pk_mul_f32 v[124:125], v[124:125], s[6:7] op_sel_hi:[1,0]
	v_pk_mul_f32 v[126:127], v[126:127], s[6:7] op_sel_hi:[1,0]
	v_pk_fma_f32 v[124:125], v[88:89], v[96:97], v[124:125]
	v_pk_fma_f32 v[126:127], v[90:91], v[98:99], v[126:127]
	global_store_dwordx4 v132, v[120:123], s[100:101]
	global_store_dwordx4 v132, v[124:127], s[100:101] offset:64
	s_add_u32 s100, s100, 0x20000
	s_addc_u32 s101, s101, 0
	v_pk_mul_f32 v[128:129], v[128:129], s[6:7] op_sel_hi:[1,0]
	v_pk_mul_f32 v[130:131], v[130:131], s[6:7] op_sel_hi:[1,0]
	v_pk_fma_f32 v[128:129], v[160:161], v[92:93], v[128:129]
	v_pk_fma_f32 v[130:131], v[162:163], v[94:95], v[130:131]
	v_pk_mul_f32 v[198:199], v[198:199], s[6:7] op_sel_hi:[1,0]
	v_pk_mul_f32 v[200:201], v[200:201], s[6:7] op_sel_hi:[1,0]
	v_pk_fma_f32 v[198:199], v[80:81], v[96:97], v[198:199]
	v_pk_fma_f32 v[200:201], v[82:83], v[98:99], v[200:201]
	global_store_dwordx4 v132, v[128:131], s[100:101]
	global_store_dwordx4 v132, v[198:201], s[100:101] offset:64
	s_add_u32 s100, s100, 0x20000
	s_addc_u32 s101, s101, 0
	v_pk_mul_f32 v[202:203], v[202:203], s[6:7] op_sel_hi:[1,0]
	v_pk_mul_f32 v[204:205], v[204:205], s[6:7] op_sel_hi:[1,0]
	v_pk_fma_f32 v[202:203], v[156:157], v[92:93], v[202:203]
	v_pk_fma_f32 v[204:205], v[158:159], v[94:95], v[204:205]
	v_pk_mul_f32 v[206:207], v[206:207], s[6:7] op_sel_hi:[1,0]
	v_pk_mul_f32 v[208:209], v[208:209], s[6:7] op_sel_hi:[1,0]
	v_pk_fma_f32 v[206:207], v[76:77], v[96:97], v[206:207]
	v_pk_fma_f32 v[208:209], v[78:79], v[98:99], v[208:209]
	global_store_dwordx4 v132, v[202:205], s[100:101]
	global_store_dwordx4 v132, v[206:209], s[100:101] offset:64
	s_add_u32 s100, s100, 0x20000
	s_addc_u32 s101, s101, 0
	v_pk_mul_f32 v[210:211], v[210:211], s[6:7] op_sel_hi:[1,0]
	v_pk_mul_f32 v[212:213], v[212:213], s[6:7] op_sel_hi:[1,0]
; __device__ __forceinline__ void phase_outproj(const Params& p, char* smem) {
;     ...
;     const int b = (mt * 256) >> 14;
; #pragma unroll
;     for (int n = 0; n < 4; ++n) {
;       const int col = nt * 128 + wc * 64 + n * 16 + fq * 4;
;       const float4 g1 = *(const float4*)(mod + b * 12288 + 4096 + col);
; #pragma unroll
;       for (int m = 0; m < 8; ++m) {
;         const size_t row = (size_t)mt * 256 + wr * 128 + m * 16 + fr;
;         const float4 xv = *(const float4*)(p.x + row * D + col);
;         float4 o;
;         o.x = ALPHA * xv.x + (1.f + g1.x) * acc[m][n][0];
;         o.y = ALPHA * xv.y + (1.f + g1.y) * acc[m][n][1];
;         o.z = ALPHA * xv.z + (1.f + g1.z) * acc[m][n][2];
;         o.w = ALPHA * xv.w + (1.f + g1.w) * acc[m][n][3];
;         *(float4*)(p.out + row * D + col) = o;
;       }
;     }
	v_pk_fma_f32 v[210:211], v[144:145], v[92:93], v[210:211]
	v_pk_fma_f32 v[212:213], v[146:147], v[94:95], v[212:213]
	v_pk_mul_f32 v[220:221], v[220:221], s[6:7] op_sel_hi:[1,0]
	v_pk_mul_f32 v[222:223], v[222:223], s[6:7] op_sel_hi:[1,0]
	v_pk_fma_f32 v[220:221], v[68:69], v[96:97], v[220:221]
	v_pk_fma_f32 v[222:223], v[70:71], v[98:99], v[222:223]
	global_store_dwordx4 v132, v[210:213], s[100:101]
	global_store_dwordx4 v132, v[220:223], s[100:101] offset:64
	s_add_u32 s100, s100, 0x20000
	s_addc_u32 s101, s101, 0
	v_pk_mul_f32 v[224:225], v[224:225], s[6:7] op_sel_hi:[1,0]
	v_pk_mul_f32 v[226:227], v[226:227], s[6:7] op_sel_hi:[1,0]
	v_pk_fma_f32 v[224:225], v[100:101], v[92:93], v[224:225]
	v_pk_fma_f32 v[226:227], v[102:103], v[94:95], v[226:227]
	v_pk_mul_f32 v[228:229], v[228:229], s[6:7] op_sel_hi:[1,0]
	v_pk_mul_f32 v[230:231], v[230:231], s[6:7] op_sel_hi:[1,0]
	v_pk_fma_f32 v[228:229], v[60:61], v[96:97], v[228:229]
	v_pk_fma_f32 v[230:231], v[62:63], v[98:99], v[230:231]
	global_store_dwordx4 v132, v[224:227], s[100:101]
	global_store_dwordx4 v132, v[228:231], s[100:101] offset:64
	s_add_u32 s100, s100, 0x20000
	s_addc_u32 s101, s101, 0
	v_pk_mul_f32 v[232:233], v[232:233], s[6:7] op_sel_hi:[1,0]
	v_pk_mul_f32 v[234:235], v[234:235], s[6:7] op_sel_hi:[1,0]
	v_pk_fma_f32 v[232:233], v[84:85], v[92:93], v[232:233]
	v_pk_fma_f32 v[234:235], v[86:87], v[94:95], v[234:235]
	v_pk_mul_f32 v[236:237], v[236:237], s[6:7] op_sel_hi:[1,0]
	v_pk_mul_f32 v[238:239], v[238:239], s[6:7] op_sel_hi:[1,0]
	v_pk_fma_f32 v[236:237], v[52:53], v[96:97], v[236:237]
	v_pk_fma_f32 v[238:239], v[54:55], v[98:99], v[238:239]
	global_store_dwordx4 v132, v[232:235], s[100:101]
	global_store_dwordx4 v132, v[236:239], s[100:101] offset:64
	s_mov_b64 s[98:99], s[8:9]
	global_load_dwordx4 v[104:107], v132, s[98:99] offset:128
	global_load_dwordx4 v[108:111], v132, s[98:99] offset:192
	s_add_u32 s98, s98, 0x20000
	s_addc_u32 s99, s99, 0
	global_load_dwordx4 v[112:115], v132, s[98:99] offset:128
	global_load_dwordx4 v[116:119], v132, s[98:99] offset:192
	s_add_u32 s98, s98, 0x20000
	s_addc_u32 s99, s99, 0
	global_load_dwordx4 v[120:123], v132, s[98:99] offset:128
	global_load_dwordx4 v[124:127], v132, s[98:99] offset:192
	s_add_u32 s98, s98, 0x20000
	s_addc_u32 s99, s99, 0
	global_load_dwordx4 v[128:131], v132, s[98:99] offset:128
	global_load_dwordx4 v[198:201], v132, s[98:99] offset:192
	s_add_u32 s98, s98, 0x20000
	s_addc_u32 s99, s99, 0
	global_load_dwordx4 v[202:205], v132, s[98:99] offset:128
	global_load_dwordx4 v[206:209], v132, s[98:99] offset:192
	s_add_u32 s98, s98, 0x20000
	s_addc_u32 s99, s99, 0
	global_load_dwordx4 v[210:213], v132, s[98:99] offset:128
	global_load_dwordx4 v[220:223], v132, s[98:99] offset:192
	s_add_u32 s98, s98, 0x20000
	s_addc_u32 s99, s99, 0
	global_load_dwordx4 v[224:227], v132, s[98:99] offset:128
	global_load_dwordx4 v[228:231], v132, s[98:99] offset:192
	s_add_u32 s98, s98, 0x20000
	s_addc_u32 s99, s99, 0
	global_load_dwordx4 v[232:235], v132, s[98:99] offset:128
	global_load_dwordx4 v[236:239], v132, s[98:99] offset:192
	s_waitcnt vmcnt(0)
; __device__ __forceinline__ void phase_outproj(const Params& p, char* smem) {
;     ...
;     for (int n = 0; n < 4; ++n) {
;       const int col = nt * 128 + wc * 64 + n * 16 + fq * 4;
;       const float4 g1 = *(const float4*)(mod + b * 12288 + 4096 + col);
; #pragma unroll
;       for (int m = 0; m < 8; ++m) {
;         const size_t row = (size_t)mt * 256 + wr * 128 + m * 16 + fr;
;         const float4 xv = *(const float4*)(p.x + row * D + col);
;         float4 o;
;         o.x = ALPHA * xv.x + (1.f + g1.x) * acc[m][n][0];
;         o.y = ALPHA * xv.y + (1.f + g1.y) * acc[m][n][1];
;         o.z = ALPHA * xv.z + (1.f + g1.z) * acc[m][n][2];
;         o.w = ALPHA * xv.w + (1.f + g1.w) * acc[m][n][3];
;         *(float4*)(p.out + row * D + col) = o;
;       }
;     }
	s_mov_b64 s[100:101], s[52:53]
	v_pk_mul_f32 v[104:105], v[104:105], s[6:7] op_sel_hi:[1,0]
	v_pk_mul_f32 v[106:107], v[106:107], s[6:7] op_sel_hi:[1,0]
	v_pk_fma_f32 v[104:105], v[72:73], v[148:149], v[104:105]
	v_pk_fma_f32 v[106:107], v[74:75], v[150:151], v[106:107]
	v_pk_mul_f32 v[108:109], v[108:109], s[6:7] op_sel_hi:[1,0]
	v_pk_mul_f32 v[110:111], v[110:111], s[6:7] op_sel_hi:[1,0]
	v_pk_fma_f32 v[108:109], v[40:41], v[136:137], v[108:109]
	v_pk_fma_f32 v[110:111], v[42:43], v[138:139], v[110:111]
	global_store_dwordx4 v132, v[104:107], s[100:101] offset:128
	global_store_dwordx4 v132, v[108:111], s[100:101] offset:192
	s_add_u32 s100, s100, 0x20000
	s_addc_u32 s101, s101, 0
	v_pk_mul_f32 v[112:113], v[112:113], s[6:7] op_sel_hi:[1,0]
	v_pk_mul_f32 v[114:115], v[114:115], s[6:7] op_sel_hi:[1,0]
	v_pk_fma_f32 v[112:113], v[64:65], v[148:149], v[112:113]
	v_pk_fma_f32 v[114:115], v[66:67], v[150:151], v[114:115]
	v_pk_mul_f32 v[116:117], v[116:117], s[6:7] op_sel_hi:[1,0]
	v_pk_mul_f32 v[118:119], v[118:119], s[6:7] op_sel_hi:[1,0]
	v_pk_fma_f32 v[116:117], v[32:33], v[136:137], v[116:117]
	v_pk_fma_f32 v[118:119], v[34:35], v[138:139], v[118:119]
	global_store_dwordx4 v132, v[112:115], s[100:101] offset:128
	global_store_dwordx4 v132, v[116:119], s[100:101] offset:192
	s_add_u32 s100, s100, 0x20000
	s_addc_u32 s101, s101, 0
	v_pk_mul_f32 v[120:121], v[120:121], s[6:7] op_sel_hi:[1,0]
	v_pk_mul_f32 v[122:123], v[122:123], s[6:7] op_sel_hi:[1,0]
	v_pk_fma_f32 v[120:121], v[56:57], v[148:149], v[120:121]
	v_pk_fma_f32 v[122:123], v[58:59], v[150:151], v[122:123]
	v_pk_mul_f32 v[124:125], v[124:125], s[6:7] op_sel_hi:[1,0]
	v_pk_mul_f32 v[126:127], v[126:127], s[6:7] op_sel_hi:[1,0]
	v_pk_fma_f32 v[124:125], v[24:25], v[136:137], v[124:125]
	v_pk_fma_f32 v[126:127], v[26:27], v[138:139], v[126:127]
	global_store_dwordx4 v132, v[120:123], s[100:101] offset:128
	global_store_dwordx4 v132, v[124:127], s[100:101] offset:192
	s_add_u32 s100, s100, 0x20000
	s_addc_u32 s101, s101, 0
	v_pk_mul_f32 v[128:129], v[128:129], s[6:7] op_sel_hi:[1,0]
	v_pk_mul_f32 v[130:131], v[130:131], s[6:7] op_sel_hi:[1,0]
	v_pk_fma_f32 v[128:129], v[48:49], v[148:149], v[128:129]
	v_pk_fma_f32 v[130:131], v[50:51], v[150:151], v[130:131]
	v_pk_mul_f32 v[198:199], v[198:199], s[6:7] op_sel_hi:[1,0]
	v_pk_mul_f32 v[200:201], v[200:201], s[6:7] op_sel_hi:[1,0]
	v_pk_fma_f32 v[198:199], v[16:17], v[136:137], v[198:199]
	v_pk_fma_f32 v[200:201], v[18:19], v[138:139], v[200:201]
	global_store_dwordx4 v132, v[128:131], s[100:101] offset:128
	global_store_dwordx4 v132, v[198:201], s[100:101] offset:192
	s_add_u32 s100, s100, 0x20000
	s_addc_u32 s101, s101, 0
	v_pk_mul_f32 v[202:203], v[202:203], s[6:7] op_sel_hi:[1,0]
	v_pk_mul_f32 v[204:205], v[204:205], s[6:7] op_sel_hi:[1,0]
	v_pk_fma_f32 v[202:203], v[44:45], v[148:149], v[202:203]
	v_pk_fma_f32 v[204:205], v[46:47], v[150:151], v[204:205]
	v_pk_mul_f32 v[206:207], v[206:207], s[6:7] op_sel_hi:[1,0]
	v_pk_mul_f32 v[208:209], v[208:209], s[6:7] op_sel_hi:[1,0]
	v_pk_fma_f32 v[206:207], v[12:13], v[136:137], v[206:207]
	v_pk_fma_f32 v[208:209], v[14:15], v[138:139], v[208:209]
	global_store_dwordx4 v132, v[202:205], s[100:101] offset:128
	global_store_dwordx4 v132, v[206:209], s[100:101] offset:192
	s_add_u32 s100, s100, 0x20000
	s_addc_u32 s101, s101, 0
	v_pk_mul_f32 v[210:211], v[210:211], s[6:7] op_sel_hi:[1,0]
	v_pk_mul_f32 v[212:213], v[212:213], s[6:7] op_sel_hi:[1,0]
	v_pk_fma_f32 v[210:211], v[36:37], v[148:149], v[210:211]
	v_pk_fma_f32 v[212:213], v[38:39], v[150:151], v[212:213]
	v_pk_mul_f32 v[220:221], v[220:221], s[6:7] op_sel_hi:[1,0]
	v_pk_mul_f32 v[222:223], v[222:223], s[6:7] op_sel_hi:[1,0]
	v_pk_fma_f32 v[220:221], v[8:9], v[136:137], v[220:221]
	v_pk_fma_f32 v[222:223], v[10:11], v[138:139], v[222:223]
	global_store_dwordx4 v132, v[210:213], s[100:101] offset:128
	global_store_dwordx4 v132, v[220:223], s[100:101] offset:192
	s_add_u32 s100, s100, 0x20000
	s_addc_u32 s101, s101, 0
	v_pk_mul_f32 v[224:225], v[224:225], s[6:7] op_sel_hi:[1,0]
	v_pk_mul_f32 v[226:227], v[226:227], s[6:7] op_sel_hi:[1,0]
	v_pk_fma_f32 v[224:225], v[28:29], v[148:149], v[224:225]
	v_pk_fma_f32 v[226:227], v[30:31], v[150:151], v[226:227]
	v_pk_mul_f32 v[228:229], v[228:229], s[6:7] op_sel_hi:[1,0]
	v_pk_mul_f32 v[230:231], v[230:231], s[6:7] op_sel_hi:[1,0]
	v_pk_fma_f32 v[228:229], v[4:5], v[136:137], v[228:229]
	v_pk_fma_f32 v[230:231], v[6:7], v[138:139], v[230:231]
	global_store_dwordx4 v132, v[224:227], s[100:101] offset:128
	global_store_dwordx4 v132, v[228:231], s[100:101] offset:192
	s_add_u32 s100, s100, 0x20000
	s_addc_u32 s101, s101, 0
	v_pk_mul_f32 v[232:233], v[232:233], s[6:7] op_sel_hi:[1,0]
	v_pk_mul_f32 v[234:235], v[234:235], s[6:7] op_sel_hi:[1,0]
	v_pk_fma_f32 v[232:233], v[20:21], v[148:149], v[232:233]
	v_pk_fma_f32 v[234:235], v[22:23], v[150:151], v[234:235]
	v_pk_mul_f32 v[236:237], v[236:237], s[6:7] op_sel_hi:[1,0]
	v_pk_mul_f32 v[238:239], v[238:239], s[6:7] op_sel_hi:[1,0]
	v_pk_fma_f32 v[236:237], v[0:1], v[136:137], v[236:237]
	v_pk_fma_f32 v[238:239], v[2:3], v[138:139], v[238:239]
	global_store_dwordx4 v132, v[232:235], s[100:101] offset:128
	global_store_dwordx4 v132, v[236:239], s[100:101] offset:192
	s_add_i32 s20, s20, s3
	s_add_i32 s11, s11, s3
	v_readlane_b32 s66, v253, 18
	v_readlane_b32 s67, v253, 19
	v_readlane_b32 s68, v253, 20
	v_readlane_b32 s69, v253, 21
	v_readlane_b32 s70, v253, 22
	v_readlane_b32 s71, v253, 23
	v_readlane_b32 s72, v253, 24
	v_readlane_b32 s73, v253, 25
	v_readlane_b32 s74, v253, 26
	v_readlane_b32 s75, v253, 27
	v_readlane_b32 s76, v253, 28
	v_readlane_b32 s77, v253, 29
	v_readlane_b32 s78, v253, 30
	v_readlane_b32 s79, v253, 31
	s_cmpk_lt_u32 s20, 0x100
	s_cbranch_scc0 .LBB0_1035

; __device__ __forceinline__ void phase_peerq(const Params& p, char* smem) {
;     ...
; #pragma unroll
;     for (int m = 0; m < 8; ++m)
; #pragma unroll
;       for (int n = 0; n < 4; ++n) {
;         const size_t row = (size_t)mt * 256 + wr * 128 + m * 16 + fr;
;         const int col = nt * 128 + wc * 64 + n * 16 + fq * 4;
;         *(float4*)(qo + row * D + col) = make_float4(acc[m][n][0], acc[m][n][1], acc[m][n][2], acc[m][n][3]);
;       }
.LBB0_1070:
	s_setprio 3
	s_lshl_b32 s0, s48, 21
	s_waitcnt vmcnt(11)
	v_lshl_add_u64 v[0:1], v[176:177], 0, s[0:1]
	v_lshl_or_b32 v178, s47, 9, v192
	v_lshl_add_u64 v[2:3], v[0:1], 0, v[178:179]
	s_barrier
	global_store_dwordx4 v[2:3], v[172:175], off
	global_store_dwordx4 v[2:3], v[168:171], off offset:64
	global_store_dwordx4 v[2:3], v[164:167], off offset:128
	global_store_dwordx4 v[2:3], v[160:163], off offset:192
	v_lshl_add_u64 v[2:3], v[0:1], 0, s[4:5]
	s_waitcnt vmcnt(14)
	v_lshl_add_u64 v[4:5], v[2:3], 0, v[178:179]
	global_store_dwordx4 v[4:5], v[156:159], off
	v_or_b32_e32 v4, 64, v178
	v_mov_b32_e32 v5, v179
	v_lshl_add_u64 v[6:7], v[2:3], 0, v[4:5]
	global_store_dwordx4 v[6:7], v[152:155], off
	v_or_b32_e32 v6, 0x80, v178
	v_mov_b32_e32 v7, v179
	s_waitcnt vmcnt(14)
	v_lshl_add_u64 v[8:9], v[2:3], 0, v[6:7]
	global_store_dwordx4 v[8:9], v[148:151], off
	v_or_b32_e32 v8, 0xc0, v178
	v_mov_b32_e32 v9, v179
	v_lshl_add_u64 v[2:3], v[2:3], 0, v[8:9]
	global_store_dwordx4 v[2:3], v[144:147], off
	v_lshl_add_u64 v[2:3], v[0:1], 0, s[6:7]
	v_lshl_add_u64 v[10:11], v[2:3], 0, v[178:179]
	global_store_dwordx4 v[10:11], v[140:143], off
	v_lshl_add_u64 v[10:11], v[2:3], 0, v[4:5]
	global_store_dwordx4 v[10:11], v[136:139], off
	v_lshl_add_u64 v[10:11], v[2:3], 0, v[6:7]
	v_lshl_add_u64 v[2:3], v[2:3], 0, v[8:9]
	global_store_dwordx4 v[2:3], v[128:131], off
	v_lshl_add_u64 v[2:3], v[0:1], 0, s[8:9]
	global_store_dwordx4 v[10:11], v[132:135], off
	v_lshl_add_u64 v[10:11], v[2:3], 0, v[178:179]
	global_store_dwordx4 v[10:11], v[124:127], off
	v_lshl_add_u64 v[10:11], v[2:3], 0, v[4:5]
	global_store_dwordx4 v[10:11], v[120:123], off
	v_lshl_add_u64 v[10:11], v[2:3], 0, v[6:7]
	v_lshl_add_u64 v[2:3], v[2:3], 0, v[8:9]
	global_store_dwordx4 v[2:3], v[112:115], off
	v_lshl_add_u64 v[2:3], v[0:1], 0, s[10:11]
	global_store_dwordx4 v[10:11], v[116:119], off
	v_lshl_add_u64 v[10:11], v[2:3], 0, v[178:179]
	global_store_dwordx4 v[10:11], v[108:111], off
	v_lshl_add_u64 v[10:11], v[2:3], 0, v[4:5]
	global_store_dwordx4 v[10:11], v[104:107], off
	v_lshl_add_u64 v[10:11], v[2:3], 0, v[6:7]
	v_lshl_add_u64 v[2:3], v[2:3], 0, v[8:9]
	global_store_dwordx4 v[2:3], v[96:99], off
	v_lshl_add_u64 v[2:3], v[0:1], 0, s[12:13]
	global_store_dwordx4 v[10:11], v[100:103], off
	v_lshl_add_u64 v[10:11], v[2:3], 0, v[178:179]
	global_store_dwordx4 v[10:11], v[92:95], off
	v_lshl_add_u64 v[10:11], v[2:3], 0, v[4:5]
	global_store_dwordx4 v[10:11], v[88:91], off
	v_lshl_add_u64 v[10:11], v[2:3], 0, v[6:7]
	v_lshl_add_u64 v[2:3], v[2:3], 0, v[8:9]
	global_store_dwordx4 v[2:3], v[80:83], off
	v_lshl_add_u64 v[2:3], v[0:1], 0, s[14:15]
	global_store_dwordx4 v[10:11], v[84:87], off
	v_lshl_add_u64 v[10:11], v[2:3], 0, v[178:179]
	global_store_dwordx4 v[10:11], v[76:79], off
	v_lshl_add_u64 v[10:11], v[2:3], 0, v[4:5]
	global_store_dwordx4 v[10:11], v[72:75], off
	v_lshl_add_u64 v[10:11], v[2:3], 0, v[6:7]
	v_lshl_add_u64 v[2:3], v[2:3], 0, v[8:9]
	v_lshl_add_u64 v[0:1], v[0:1], 0, s[16:17]
	global_store_dwordx4 v[2:3], v[64:67], off
	v_lshl_add_u64 v[2:3], v[0:1], 0, v[178:179]
	global_store_dwordx4 v[2:3], v[60:63], off
	v_lshl_add_u64 v[2:3], v[0:1], 0, v[4:5]
	s_add_i32 s62, s62, s3
	s_add_i32 s24, s24, s3
	global_store_dwordx4 v[2:3], v[52:55], off
	v_lshl_add_u64 v[2:3], v[0:1], 0, v[6:7]
	v_lshl_add_u64 v[0:1], v[0:1], 0, v[8:9]
	s_cmpk_lt_u32 s62, 0x100
	global_store_dwordx4 v[10:11], v[68:71], off
	global_store_dwordx4 v[2:3], v[56:59], off
	global_store_dwordx4 v[0:1], v[48:51], off
	s_cbranch_scc0 .LBB0_1075
